# attention PV gaps: removed the 12 compiler inline-asm pads (s_nop 0) per tile iteration that guard no real hazard
# speedup vs baseline: 1.0364x; 1.0094x over previous
.LBB0_188:
	s_waitcnt lgkmcnt(0)
	v_mfma_f32_32x32x16_bf16 v[34:49], v[126:129], v[162:165], v[34:49]
	ds_read_b128 v[126:129], v212 offset:49152
	s_nop 0
	v_exp_f32_e32 v130, v82
	v_exp_f32_e32 v131, v83
	v_add_f32_e32 v132, v1, v130
	v_add_f32_e32 v133, v1, v131
	v_cvt_pk_bf16_f32 v166, v130, v131
	v_mfma_f32_32x32x16_bf16 v[50:65], v[122:125], v[162:165], v[50:65]
	ds_read_b128 v[122:125], v212 offset:53248
	v_exp_f32_e32 v134, v84
	v_exp_f32_e32 v135, v85
	s_add_i32 s22, s23, 2
	s_cmp_lt_u32 s22, s17
	v_add_f32_e32 v130, v132, v134
	v_add_f32_e32 v131, v133, v135
	v_cvt_pk_bf16_f32 v167, v134, v135
	s_cselect_b64 s[26:27], -1, 0
	s_cmp_ge_u32 s22, s17
	s_cbranch_scc1 .LBB0_190
	v_lshl_add_u64 v[132:133], s[8:9], 0, v[214:215]
	s_lshl_b32 s40, s48, 14
	v_lshl_add_u64 v[132:133], v[132:133], 0, s[80:81]
	s_add_i32 m0, s11, s40
	s_nop 0
	global_load_lds_dwordx4 v[132:133], off
.LBB0_190:
	v_mfma_f32_32x32x16_bf16 v[18:33], v[118:121], v[162:165], v[18:33]
	ds_read_b128 v[118:121], v212 offset:57344
	v_exp_f32_e32 v132, v86
	v_exp_f32_e32 v133, v87
	v_add_f32_e32 v130, v130, v132
	v_add_f32_e32 v131, v131, v133
	v_cvt_pk_bf16_f32 v168, v132, v133
	v_mfma_f32_32x32x16_bf16 v[2:17], v[114:117], v[162:165], v[2:17]
	ds_read_b128 v[114:117], v212 offset:61440
	v_exp_f32_e32 v132, v88
	v_exp_f32_e32 v133, v89
	v_add_f32_e32 v134, v130, v132
	v_add_f32_e32 v131, v131, v133
	v_cvt_pk_bf16_f32 v169, v132, v133
	s_waitcnt lgkmcnt(0)
	v_mfma_f32_32x32x16_bf16 v[34:49], v[126:129], v[170:173], v[34:49]
	v_add_u32_e32 v130, s54, v246
	ds_read_b128 v[126:129], v130 offset:49152
	v_exp_f32_e32 v132, v90
	v_exp_f32_e32 v133, v91
	v_add_f32_e32 v134, v134, v132
	v_add_f32_e32 v135, v131, v133
	v_cvt_pk_bf16_f32 v174, v132, v133
	v_mfma_f32_32x32x16_bf16 v[50:65], v[122:125], v[170:173], v[50:65]
	ds_read_b128 v[122:125], v130 offset:53248
	v_exp_f32_e32 v133, v92
	v_exp_f32_e32 v136, v93
	v_add_f32_e32 v131, v134, v133
	v_add_f32_e32 v132, v135, v136
	s_andn2_b64 vcc, exec, s[26:27]
	v_cvt_pk_bf16_f32 v175, v133, v136
	s_cbranch_vccnz .LBB0_192
	s_lshl_b32 s26, s48, 14
	v_lshl_add_u64 v[134:135], s[8:9], 0, v[214:215]
	s_add_i32 s26, s11, s26
	v_lshl_add_u64 v[134:135], v[134:135], 0, s[62:63]
	s_add_i32 m0, s26, 0x2000
	s_nop 0
	global_load_lds_dwordx4 v[134:135], off
.LBB0_192:
	v_mfma_f32_32x32x16_bf16 v[18:33], v[118:121], v[170:173], v[18:33]
	ds_read_b128 v[118:121], v130 offset:57344
	v_exp_f32_e32 v133, v94
	v_exp_f32_e32 v134, v95
	v_add_f32_e32 v131, v131, v133
	v_add_f32_e32 v132, v132, v134
	v_cvt_pk_bf16_f32 v176, v133, v134
	v_mfma_f32_32x32x16_bf16 v[2:17], v[114:117], v[170:173], v[2:17]
	ds_read_b128 v[114:117], v130 offset:61440
	v_exp_f32_e32 v130, v96
	v_exp_f32_e32 v133, v97
	v_add_f32_e32 v131, v131, v130
	v_add_f32_e32 v132, v132, v133
	v_cvt_pk_bf16_f32 v177, v130, v133
	s_waitcnt lgkmcnt(0)
	v_mfma_f32_32x32x16_bf16 v[34:49], v[126:129], v[178:181], v[34:49]
	v_add_u32_e32 v130, s54, v247
	ds_read_b128 v[126:129], v130 offset:49152
	v_exp_f32_e32 v133, v98
	v_exp_f32_e32 v134, v99
	v_add_f32_e32 v131, v131, v133
	v_add_f32_e32 v132, v132, v134
	v_cvt_pk_bf16_f32 v182, v133, v134
	v_mfma_f32_32x32x16_bf16 v[50:65], v[122:125], v[178:181], v[50:65]
	v_exp_f32_e32 v133, v100
	v_exp_f32_e32 v134, v101
	ds_read_b128 v[122:125], v130 offset:53248
	v_add_f32_e32 v131, v131, v133
	v_add_f32_e32 v132, v132, v134
	v_cvt_pk_bf16_f32 v183, v133, v134
	v_cndmask_b32_e64 v133, 0, 1, s[88:89]
	v_cmp_ne_u32_e64 s[40:41], 1, v133
	s_andn2_b64 vcc, exec, s[88:89]
	s_cbranch_vccnz .LBB0_194
	s_lshl_b32 s26, s31, 14
	v_lshl_add_u64 v[134:135], s[8:9], 0, v[216:217]
	s_add_i32 s26, s11, s26
	v_lshl_add_u64 v[134:135], v[134:135], 0, s[96:97]
	s_add_i32 m0, s26, 0xc000
	s_nop 0
	global_load_lds_dwordx4 v[134:135], off
.LBB0_194:
	v_mfma_f32_32x32x16_bf16 v[18:33], v[118:121], v[178:181], v[18:33]
	ds_read_b128 v[118:121], v130 offset:57344
	v_exp_f32_e32 v133, v102
	v_exp_f32_e32 v134, v103
	v_add_f32_e32 v131, v131, v133
	v_add_f32_e32 v132, v132, v134
	v_cvt_pk_bf16_f32 v184, v133, v134
	v_mfma_f32_32x32x16_bf16 v[2:17], v[114:117], v[178:181], v[2:17]
	ds_read_b128 v[114:117], v130 offset:61440
	v_exp_f32_e32 v130, v104
	v_exp_f32_e32 v133, v105
	v_add_f32_e32 v131, v131, v130
	v_add_f32_e32 v132, v132, v133
	v_cvt_pk_bf16_f32 v185, v130, v133
	s_waitcnt lgkmcnt(0)
	v_mfma_f32_32x32x16_bf16 v[34:49], v[126:129], v[186:189], v[34:49]
	v_exp_f32_e32 v126, v106
	v_exp_f32_e32 v127, v107
	v_add_f32_e32 v128, v131, v126
	v_add_f32_e32 v129, v132, v127
	v_cvt_pk_bf16_f32 v190, v126, v127
	v_mfma_f32_32x32x16_bf16 v[50:65], v[122:125], v[186:189], v[50:65]
	v_exp_f32_e32 v124, v108
	v_exp_f32_e32 v125, v109
	v_add_f32_e32 v122, v128, v124
	v_add_f32_e32 v123, v129, v125
	s_and_b64 vcc, exec, s[40:41]
	v_cvt_pk_bf16_f32 v191, v124, v125
	s_cbranch_vccnz .LBB0_196
	s_lshl_b32 s26, s31, 14
	v_lshl_add_u64 v[124:125], s[8:9], 0, v[216:217]
	s_add_i32 s26, s11, s26
	v_lshl_add_u64 v[124:125], v[124:125], 0, s[58:59]
	s_add_i32 m0, s26, 0xe000
	s_nop 0
	global_load_lds_dwordx4 v[124:125], off
.LBB0_196:
	v_mfma_f32_32x32x16_bf16 v[18:33], v[118:121], v[186:189], v[18:33]
	v_exp_f32_e32 v118, v110
	v_exp_f32_e32 v119, v111
	v_add_f32_e32 v120, v122, v118
	v_add_f32_e32 v121, v123, v119
	v_cvt_pk_bf16_f32 v192, v118, v119
	v_mfma_f32_32x32x16_bf16 v[2:17], v[114:117], v[186:189], v[2:17]
	v_exp_f32_e32 v114, v112
	v_exp_f32_e32 v115, v113
	v_add_f32_e32 v116, v120, v114
	v_add_f32_e32 v117, v121, v115
	v_cvt_pk_bf16_f32 v193, v114, v115
	s_nop 0
	v_add_f32_e32 v212, v116, v117
	v_cmp_nge_f32_e32 vcc, s7, v212
	s_cbranch_vccz .LBB0_198
	v_max_f32_e32 v66, v99, v99
	v_max_f32_e32 v67, v83, v83
	v_max_f32_e32 v66, v67, v66
	v_max3_f32 v66, v82, v98, v66
	v_max3_f32 v67, v100, v85, v101
	v_max3_f32 v66, v66, v84, v67
	v_max3_f32 v67, v102, v87, v103
	v_max3_f32 v66, v66, v86, v67
	v_max3_f32 v67, v104, v89, v105
	v_max3_f32 v66, v66, v88, v67
	v_max3_f32 v67, v106, v91, v107
	v_max3_f32 v66, v66, v90, v67
	v_max3_f32 v67, v108, v93, v109
	v_max3_f32 v66, v66, v92, v67
	v_max3_f32 v67, v110, v95, v111
	v_max3_f32 v66, v66, v94, v67
	v_max3_f32 v67, v112, v97, v113
	v_max3_f32 v66, v66, v96, v67
	v_mov_b32_e32 v67, v66
	s_nop 1
	v_permlane32_swap_b32_e32 v66, v67
	v_max_f32_e32 v67, v67, v67
	v_max_f32_e32 v66, v66, v66
	v_max_f32_e32 v66, v66, v67
	v_cmp_lt_f32_e32 vcc, s57, v66
	s_nop 1
	v_cndmask_b32_e32 v68, 0, v66, vcc
	v_sub_f32_e32 v66, v82, v68
	v_exp_f32_e32 v116, v66
	v_sub_f32_e32 v66, v98, v68
	v_exp_f32_e32 v117, v66
	v_sub_f32_e32 v66, v83, v68
	v_exp_f32_e32 v118, v66
	v_sub_f32_e32 v66, v99, v68
	v_exp_f32_e32 v119, v66
	v_sub_f32_e32 v66, v84, v68
	v_exp_f32_e32 v98, v66
	v_sub_f32_e32 v66, v100, v68
	v_exp_f32_e32 v82, v66
	v_add_f32_e32 v66, v117, v116
	v_add_f32_e32 v99, 0, v66
	v_add_f32_e32 v83, v119, v118
	v_pk_add_f32 v[66:67], v[82:83], v[98:99]
	v_cvt_pk_bf16_f32 v166, v116, v118
	v_pk_add_f32 v[114:115], v[66:67], v[66:67] op_sel_hi:[0,1]
	v_sub_f32_e32 v66, v85, v68
	v_exp_f32_e32 v83, v66
	v_sub_f32_e32 v66, v101, v68
	v_exp_f32_e32 v99, v66
	v_sub_f32_e32 v66, v86, v68
	v_exp_f32_e32 v114, v66
	v_sub_f32_e32 v66, v102, v68
	v_exp_f32_e32 v84, v66
	v_add_f32_e32 v85, v99, v83
	v_cvt_pk_bf16_f32 v167, v98, v83
	v_cvt_pk_bf16_f32 v182, v117, v119
	v_pk_add_f32 v[66:67], v[84:85], v[114:115]
	v_cvt_pk_bf16_f32 v183, v82, v99
	v_pk_add_f32 v[100:101], v[66:67], v[66:67] op_sel_hi:[0,1]
	v_sub_f32_e32 v66, v87, v68
	v_exp_f32_e32 v85, v66
	v_sub_f32_e32 v66, v103, v68
	v_exp_f32_e32 v115, v66
	v_sub_f32_e32 v66, v88, v68
	v_exp_f32_e32 v100, v66
	v_sub_f32_e32 v66, v104, v68
	v_exp_f32_e32 v86, v66
	v_add_f32_e32 v87, v115, v85
	v_cvt_pk_bf16_f32 v168, v114, v85
	v_cvt_pk_bf16_f32 v184, v84, v115
	v_pk_add_f32 v[66:67], v[86:87], v[100:101]
	s_nop 0
	v_pk_add_f32 v[102:103], v[66:67], v[66:67] op_sel_hi:[0,1]
	v_sub_f32_e32 v66, v89, v68
	v_exp_f32_e32 v87, v66
	v_sub_f32_e32 v66, v105, v68
	v_exp_f32_e32 v101, v66
	v_sub_f32_e32 v66, v90, v68
	v_exp_f32_e32 v102, v66
	v_sub_f32_e32 v66, v106, v68
	v_exp_f32_e32 v88, v66
	v_add_f32_e32 v89, v101, v87
	v_cvt_pk_bf16_f32 v169, v100, v87
	v_cvt_pk_bf16_f32 v185, v86, v101
	v_pk_add_f32 v[66:67], v[88:89], v[102:103]
	s_nop 0
	v_pk_add_f32 v[104:105], v[66:67], v[66:67] op_sel_hi:[0,1]
	v_sub_f32_e32 v66, v91, v68
	v_exp_f32_e32 v89, v66
	v_sub_f32_e32 v66, v107, v68
	v_exp_f32_e32 v103, v66
	v_sub_f32_e32 v66, v92, v68
	v_exp_f32_e32 v104, v66
	v_sub_f32_e32 v66, v108, v68
	v_exp_f32_e32 v90, v66
	v_sub_f32_e32 v66, v97, v68
	v_add_f32_e32 v91, v103, v89
	v_exp_f32_e32 v97, v66
	v_pk_add_f32 v[66:67], v[90:91], v[104:105]
	v_cvt_pk_bf16_f32 v174, v102, v89
	v_pk_add_f32 v[106:107], v[66:67], v[66:67] op_sel_hi:[0,1]
	v_sub_f32_e32 v66, v93, v68
	v_exp_f32_e32 v91, v66
	v_sub_f32_e32 v66, v109, v68
	v_exp_f32_e32 v105, v66
	v_sub_f32_e32 v66, v94, v68
	v_exp_f32_e32 v106, v66
	v_sub_f32_e32 v66, v110, v68
	v_exp_f32_e32 v92, v66
	v_sub_f32_e32 v66, v113, v68
	v_add_f32_e32 v93, v105, v91
	v_exp_f32_e32 v110, v66
	v_pk_add_f32 v[66:67], v[92:93], v[106:107]
	v_cvt_pk_bf16_f32 v175, v104, v91
	v_pk_add_f32 v[108:109], v[66:67], v[66:67] op_sel_hi:[0,1]
	v_sub_f32_e32 v66, v95, v68
	v_exp_f32_e32 v93, v66
	v_sub_f32_e32 v66, v111, v68
	v_exp_f32_e32 v107, v66
	v_sub_f32_e32 v66, v96, v68
	v_exp_f32_e32 v108, v66
	v_sub_f32_e32 v66, v112, v68
	v_exp_f32_e32 v94, v66
	v_add_f32_e32 v95, v107, v93
	v_exp_f32_e64 v96, -v68
	v_add_f32_e32 v212, v110, v97
	v_pk_add_f32 v[66:67], v[94:95], v[108:109]
	v_cvt_pk_bf16_f32 v176, v106, v93
	v_pk_add_f32 v[66:67], v[66:67], v[66:67] op_sel:[0,1] op_sel_hi:[1,0]
	v_pk_mul_f32 v[48:49], v[48:49], v[96:97] op_sel_hi:[1,0]
	v_mov_b32_e32 v67, v68
	v_pk_add_f32 v[212:213], v[212:213], v[66:67]
	v_pk_mul_f32 v[46:47], v[46:47], v[96:97] op_sel_hi:[1,0]
	v_xor_b32_e32 v66, 0x80000000, v213
	v_mov_b32_e32 v67, v66
	v_mov_b32_e32 v68, v66
	v_mov_b32_e32 v69, v66
	v_mov_b32_e32 v70, v66
	v_mov_b32_e32 v71, v66
	v_mov_b32_e32 v72, v66
	v_mov_b32_e32 v73, v66
	v_mov_b32_e32 v74, v66
	v_mov_b32_e32 v75, v66
	v_mov_b32_e32 v76, v66
	v_mov_b32_e32 v77, v66
	v_mov_b32_e32 v78, v66
	v_mov_b32_e32 v79, v66
	v_mov_b32_e32 v80, v66
	v_mov_b32_e32 v81, v66
	v_pk_mul_f32 v[44:45], v[44:45], v[96:97] op_sel_hi:[1,0]
	v_pk_mul_f32 v[42:43], v[42:43], v[96:97] op_sel_hi:[1,0]
	v_pk_mul_f32 v[40:41], v[40:41], v[96:97] op_sel_hi:[1,0]
	v_pk_mul_f32 v[38:39], v[38:39], v[96:97] op_sel_hi:[1,0]
	v_pk_mul_f32 v[36:37], v[36:37], v[96:97] op_sel_hi:[1,0]
	v_pk_mul_f32 v[34:35], v[34:35], v[96:97] op_sel_hi:[1,0]
	v_pk_mul_f32 v[64:65], v[64:65], v[96:97] op_sel_hi:[1,0]
	v_pk_mul_f32 v[62:63], v[62:63], v[96:97] op_sel_hi:[1,0]
	v_pk_mul_f32 v[60:61], v[60:61], v[96:97] op_sel_hi:[1,0]
	v_pk_mul_f32 v[58:59], v[58:59], v[96:97] op_sel_hi:[1,0]
	v_pk_mul_f32 v[56:57], v[56:57], v[96:97] op_sel_hi:[1,0]
	v_pk_mul_f32 v[54:55], v[54:55], v[96:97] op_sel_hi:[1,0]
	v_pk_mul_f32 v[52:53], v[52:53], v[96:97] op_sel_hi:[1,0]
	v_pk_mul_f32 v[50:51], v[50:51], v[96:97] op_sel_hi:[1,0]
	v_pk_mul_f32 v[32:33], v[32:33], v[96:97] op_sel_hi:[1,0]
	v_pk_mul_f32 v[30:31], v[30:31], v[96:97] op_sel_hi:[1,0]
	v_pk_mul_f32 v[28:29], v[28:29], v[96:97] op_sel_hi:[1,0]
	v_pk_mul_f32 v[26:27], v[26:27], v[96:97] op_sel_hi:[1,0]
	v_pk_mul_f32 v[24:25], v[24:25], v[96:97] op_sel_hi:[1,0]
	v_pk_mul_f32 v[22:23], v[22:23], v[96:97] op_sel_hi:[1,0]
	v_pk_mul_f32 v[20:21], v[20:21], v[96:97] op_sel_hi:[1,0]
	v_pk_mul_f32 v[18:19], v[18:19], v[96:97] op_sel_hi:[1,0]
	v_pk_mul_f32 v[16:17], v[16:17], v[96:97] op_sel_hi:[1,0]
	v_pk_mul_f32 v[14:15], v[14:15], v[96:97] op_sel_hi:[1,0]
	v_pk_mul_f32 v[12:13], v[12:13], v[96:97] op_sel_hi:[1,0]
	v_pk_mul_f32 v[10:11], v[10:11], v[96:97] op_sel_hi:[1,0]
	v_pk_mul_f32 v[8:9], v[8:9], v[96:97] op_sel_hi:[1,0]
	v_pk_mul_f32 v[6:7], v[6:7], v[96:97] op_sel_hi:[1,0]
	v_pk_mul_f32 v[4:5], v[4:5], v[96:97] op_sel_hi:[1,0]
	v_pk_mul_f32 v[2:3], v[2:3], v[96:97] op_sel_hi:[1,0]
	v_mul_f32_e32 v242, v242, v96
	v_cvt_pk_bf16_f32 v177, v108, v97
	v_cvt_pk_bf16_f32 v190, v88, v103
	v_cvt_pk_bf16_f32 v191, v90, v105
	v_cvt_pk_bf16_f32 v192, v92, v107
	v_cvt_pk_bf16_f32 v193, v94, v110

.LBB0_228:
	s_waitcnt lgkmcnt(0)
	v_mfma_f32_32x32x16_bf16 v[34:49], v[126:129], v[166:169], v[34:49]
	ds_read_b128 v[126:129], v212 offset:49152
	s_nop 0
	v_exp_f32_e32 v130, v82
	v_exp_f32_e32 v131, v83
	v_add_f32_e32 v132, v1, v130
	v_add_f32_e32 v133, v1, v131
	v_cvt_pk_bf16_f32 v162, v130, v131
	v_mfma_f32_32x32x16_bf16 v[50:65], v[122:125], v[166:169], v[50:65]
	ds_read_b128 v[122:125], v212 offset:53248
	v_exp_f32_e32 v130, v84
	v_exp_f32_e32 v131, v85
	s_add_i32 s23, s23, 3
	s_cmp_le_u32 s23, s16
	v_add_f32_e32 v132, v132, v130
	v_add_f32_e32 v133, v133, v131
	v_cvt_pk_bf16_f32 v163, v130, v131
	s_cselect_b64 s[26:27], -1, 0
	s_cmp_gt_u32 s23, s16
	v_lshl_add_u64 v[130:131], s[8:9], 0, v[214:215]
	s_cbranch_scc1 .LBB0_230
	s_lshl_b32 s23, s48, 14
	v_lshl_add_u64 v[134:135], v[130:131], 0, s[50:51]
	s_add_i32 m0, s11, s23
	s_nop 0
	global_load_lds_dwordx4 v[134:135], off
.LBB0_230:
	v_mfma_f32_32x32x16_bf16 v[18:33], v[118:121], v[166:169], v[18:33]
	ds_read_b128 v[118:121], v212 offset:57344
	v_exp_f32_e32 v134, v86
	v_exp_f32_e32 v135, v87
	v_add_f32_e32 v132, v132, v134
	v_add_f32_e32 v133, v133, v135
	v_cvt_pk_bf16_f32 v164, v134, v135
	v_mfma_f32_32x32x16_bf16 v[2:17], v[114:117], v[166:169], v[2:17]
	ds_read_b128 v[114:117], v212 offset:61440
	v_exp_f32_e32 v134, v88
	v_exp_f32_e32 v135, v89
	v_add_f32_e32 v136, v132, v134
	v_add_f32_e32 v133, v133, v135
	v_cvt_pk_bf16_f32 v165, v134, v135
	s_waitcnt lgkmcnt(0)
	v_mfma_f32_32x32x16_bf16 v[34:49], v[126:129], v[174:177], v[34:49]
	v_add_u32_e32 v132, s54, v246
	ds_read_b128 v[126:129], v132 offset:49152
	v_exp_f32_e32 v134, v90
	v_exp_f32_e32 v135, v91
	v_add_f32_e32 v136, v136, v134
	v_add_f32_e32 v137, v133, v135
	v_cvt_pk_bf16_f32 v170, v134, v135
	v_mfma_f32_32x32x16_bf16 v[50:65], v[122:125], v[174:177], v[50:65]
	ds_read_b128 v[122:125], v132 offset:53248
	v_exp_f32_e32 v135, v92
	v_exp_f32_e32 v138, v93
	v_add_f32_e32 v133, v136, v135
	v_add_f32_e32 v134, v137, v138
	s_andn2_b64 vcc, exec, s[26:27]
	v_cvt_pk_bf16_f32 v171, v135, v138
	s_cbranch_vccnz .LBB0_232
	s_lshl_b32 s23, s48, 14
	s_add_i32 s23, s11, s23
	v_lshl_add_u64 v[130:131], v[130:131], 0, s[4:5]
	s_add_i32 m0, s23, 0x2000
	s_nop 0
	global_load_lds_dwordx4 v[130:131], off
.LBB0_232:
	v_mfma_f32_32x32x16_bf16 v[18:33], v[118:121], v[174:177], v[18:33]
	ds_read_b128 v[118:121], v132 offset:57344
	v_exp_f32_e32 v130, v94
	v_exp_f32_e32 v131, v95
	v_add_f32_e32 v133, v133, v130
	v_add_f32_e32 v134, v134, v131
	v_cvt_pk_bf16_f32 v172, v130, v131
	v_mfma_f32_32x32x16_bf16 v[2:17], v[114:117], v[174:177], v[2:17]
	ds_read_b128 v[114:117], v132 offset:61440
	v_exp_f32_e32 v130, v96
	v_exp_f32_e32 v131, v97
	v_add_f32_e32 v133, v133, v130
	v_add_f32_e32 v134, v134, v131
	v_cvt_pk_bf16_f32 v173, v130, v131
	s_waitcnt lgkmcnt(0)
	v_mfma_f32_32x32x16_bf16 v[34:49], v[126:129], v[182:185], v[34:49]
	v_add_u32_e32 v132, s54, v247
	ds_read_b128 v[126:129], v132 offset:49152
	v_exp_f32_e32 v130, v98
	v_exp_f32_e32 v131, v99
	v_add_f32_e32 v133, v133, v130
	v_add_f32_e32 v134, v134, v131
	v_cvt_pk_bf16_f32 v178, v130, v131
	v_mfma_f32_32x32x16_bf16 v[50:65], v[122:125], v[182:185], v[50:65]
	v_exp_f32_e32 v130, v100
	v_exp_f32_e32 v131, v101
	ds_read_b128 v[122:125], v132 offset:53248
	v_add_f32_e32 v133, v133, v130
	v_add_f32_e32 v134, v134, v131
	v_cvt_pk_bf16_f32 v179, v130, v131
	v_cndmask_b32_e64 v130, 0, 1, s[88:89]
	v_cmp_ne_u32_e64 s[40:41], 1, v130
	s_andn2_b64 vcc, exec, s[88:89]
	v_lshl_add_u64 v[130:131], s[8:9], 0, v[216:217]
	s_cbranch_vccnz .LBB0_234
	s_lshl_b32 s23, s31, 14
	s_add_i32 s23, s11, s23
	v_lshl_add_u64 v[136:137], v[130:131], 0, s[0:1]
	s_add_i32 m0, s23, 0xc000
	s_nop 0
	global_load_lds_dwordx4 v[136:137], off
.LBB0_234:
	v_mfma_f32_32x32x16_bf16 v[18:33], v[118:121], v[182:185], v[18:33]
	ds_read_b128 v[118:121], v132 offset:57344
	v_exp_f32_e32 v135, v102
	v_exp_f32_e32 v136, v103
	v_add_f32_e32 v133, v133, v135
	v_add_f32_e32 v134, v134, v136
	v_cvt_pk_bf16_f32 v180, v135, v136
	v_mfma_f32_32x32x16_bf16 v[2:17], v[114:117], v[182:185], v[2:17]
	ds_read_b128 v[114:117], v132 offset:61440
	v_exp_f32_e32 v132, v104
	v_exp_f32_e32 v135, v105
	v_add_f32_e32 v133, v133, v132
	v_add_f32_e32 v134, v134, v135
	v_cvt_pk_bf16_f32 v181, v132, v135
	s_waitcnt lgkmcnt(0)
	v_mfma_f32_32x32x16_bf16 v[34:49], v[126:129], v[190:193], v[34:49]
	v_exp_f32_e32 v126, v106
	v_exp_f32_e32 v127, v107
	v_add_f32_e32 v128, v133, v126
	v_add_f32_e32 v129, v134, v127
	v_cvt_pk_bf16_f32 v186, v126, v127
	v_mfma_f32_32x32x16_bf16 v[50:65], v[122:125], v[190:193], v[50:65]
	v_exp_f32_e32 v124, v108
	v_exp_f32_e32 v125, v109
	v_add_f32_e32 v122, v128, v124
	v_add_f32_e32 v123, v129, v125
	s_and_b64 vcc, exec, s[40:41]
	v_cvt_pk_bf16_f32 v187, v124, v125
	s_cbranch_vccnz .LBB0_236
	s_lshl_b32 s23, s31, 14
	s_add_i32 s23, s11, s23
	v_lshl_add_u64 v[124:125], v[130:131], 0, s[52:53]
	s_add_i32 m0, s23, 0xe000
	s_nop 0
	global_load_lds_dwordx4 v[124:125], off
.LBB0_236:
	v_mfma_f32_32x32x16_bf16 v[18:33], v[118:121], v[190:193], v[18:33]
	v_exp_f32_e32 v118, v110
	v_exp_f32_e32 v119, v111
	v_add_f32_e32 v120, v122, v118
	v_add_f32_e32 v121, v123, v119
	v_cvt_pk_bf16_f32 v188, v118, v119
	v_mfma_f32_32x32x16_bf16 v[2:17], v[114:117], v[190:193], v[2:17]
	v_exp_f32_e32 v114, v112
	v_exp_f32_e32 v115, v113
	v_add_f32_e32 v116, v120, v114
	v_add_f32_e32 v117, v121, v115
	v_cvt_pk_bf16_f32 v189, v114, v115
	s_nop 0
	v_add_f32_e32 v212, v116, v117
	v_cmp_nge_f32_e32 vcc, s7, v212
	s_cbranch_vccz .LBB0_238
	v_max_f32_e32 v66, v99, v99
	v_max_f32_e32 v67, v83, v83
	v_max_f32_e32 v66, v67, v66
	v_max3_f32 v66, v82, v98, v66
	v_max3_f32 v67, v100, v85, v101
	v_max3_f32 v66, v66, v84, v67
	v_max3_f32 v67, v102, v87, v103
	v_max3_f32 v66, v66, v86, v67
	v_max3_f32 v67, v104, v89, v105
	v_max3_f32 v66, v66, v88, v67
	v_max3_f32 v67, v106, v91, v107
	v_max3_f32 v66, v66, v90, v67
	v_max3_f32 v67, v108, v93, v109
	v_max3_f32 v66, v66, v92, v67
	v_max3_f32 v67, v110, v95, v111
	v_max3_f32 v66, v66, v94, v67
	v_max3_f32 v67, v112, v97, v113
	v_max3_f32 v66, v66, v96, v67
	v_mov_b32_e32 v67, v66
	s_nop 1
	v_permlane32_swap_b32_e32 v66, v67
	v_max_f32_e32 v67, v67, v67
	v_max_f32_e32 v66, v66, v66
	v_max_f32_e32 v66, v66, v67
	v_cmp_lt_f32_e32 vcc, s57, v66
	s_nop 1
	v_cndmask_b32_e32 v68, 0, v66, vcc
	v_sub_f32_e32 v66, v82, v68
	v_exp_f32_e32 v116, v66
	v_sub_f32_e32 v66, v98, v68
	v_exp_f32_e32 v117, v66
	v_sub_f32_e32 v66, v83, v68
	v_exp_f32_e32 v118, v66
	v_sub_f32_e32 v66, v99, v68
	v_exp_f32_e32 v119, v66
	v_sub_f32_e32 v66, v84, v68
	v_exp_f32_e32 v114, v66
	v_sub_f32_e32 v66, v100, v68
	v_exp_f32_e32 v82, v66
	v_add_f32_e32 v66, v116, v117
	v_add_f32_e32 v83, 0, v66
	v_add_f32_e32 v115, v118, v119
	v_pk_add_f32 v[66:67], v[114:115], v[82:83]
	v_cvt_pk_bf16_f32 v162, v116, v118
	v_pk_add_f32 v[98:99], v[66:67], v[66:67] op_sel_hi:[0,1]
	v_sub_f32_e32 v66, v85, v68
	v_exp_f32_e32 v83, v66
	v_sub_f32_e32 v66, v101, v68
	v_exp_f32_e32 v115, v66
	v_sub_f32_e32 v66, v86, v68
	v_exp_f32_e32 v100, v66
	v_sub_f32_e32 v66, v102, v68
	v_exp_f32_e32 v98, v66
	v_add_f32_e32 v101, v83, v115
	v_cvt_pk_bf16_f32 v163, v114, v83
	v_cvt_pk_bf16_f32 v178, v117, v119
	v_pk_add_f32 v[66:67], v[100:101], v[98:99]
	v_cvt_pk_bf16_f32 v179, v82, v115
	v_pk_add_f32 v[84:85], v[66:67], v[66:67] op_sel_hi:[0,1]
	v_sub_f32_e32 v66, v87, v68
	v_exp_f32_e32 v99, v66
	v_sub_f32_e32 v66, v103, v68
	v_exp_f32_e32 v101, v66
	v_sub_f32_e32 v66, v88, v68
	v_exp_f32_e32 v102, v66
	v_sub_f32_e32 v66, v104, v68
	v_exp_f32_e32 v84, v66
	v_add_f32_e32 v103, v99, v101
	v_cvt_pk_bf16_f32 v164, v100, v99
	v_cvt_pk_bf16_f32 v180, v98, v101
	v_pk_add_f32 v[66:67], v[102:103], v[84:85]
	s_nop 0
	v_pk_add_f32 v[86:87], v[66:67], v[66:67] op_sel_hi:[0,1]
	v_sub_f32_e32 v66, v89, v68
	v_exp_f32_e32 v85, v66
	v_sub_f32_e32 v66, v105, v68
	v_exp_f32_e32 v103, v66
	v_sub_f32_e32 v66, v90, v68
	v_exp_f32_e32 v104, v66
	v_sub_f32_e32 v66, v106, v68
	v_exp_f32_e32 v86, v66
	v_add_f32_e32 v105, v85, v103
	v_cvt_pk_bf16_f32 v165, v102, v85
	v_cvt_pk_bf16_f32 v181, v84, v103
	v_pk_add_f32 v[66:67], v[104:105], v[86:87]
	s_nop 0
	v_pk_add_f32 v[88:89], v[66:67], v[66:67] op_sel_hi:[0,1]
	v_sub_f32_e32 v66, v91, v68
	v_exp_f32_e32 v87, v66
	v_sub_f32_e32 v66, v107, v68
	v_exp_f32_e32 v105, v66
	v_sub_f32_e32 v66, v92, v68
	v_exp_f32_e32 v90, v66
	v_sub_f32_e32 v66, v108, v68
	v_exp_f32_e32 v88, v66
	v_sub_f32_e32 v66, v97, v68
	v_add_f32_e32 v91, v87, v105
	v_exp_f32_e32 v97, v66
	v_pk_add_f32 v[66:67], v[90:91], v[88:89]
	v_cvt_pk_bf16_f32 v170, v104, v87
	v_pk_add_f32 v[106:107], v[66:67], v[66:67] op_sel_hi:[0,1]
	v_sub_f32_e32 v66, v93, v68
	v_exp_f32_e32 v89, v66
	v_sub_f32_e32 v66, v109, v68
	v_exp_f32_e32 v91, v66
	v_sub_f32_e32 v66, v94, v68
	v_exp_f32_e32 v92, v66
	v_sub_f32_e32 v66, v110, v68
	v_exp_f32_e32 v106, v66
	v_sub_f32_e32 v66, v113, v68
	v_add_f32_e32 v93, v89, v91
	v_exp_f32_e32 v110, v66
	v_pk_add_f32 v[66:67], v[92:93], v[106:107]
	v_cvt_pk_bf16_f32 v171, v90, v89
	v_pk_add_f32 v[108:109], v[66:67], v[66:67] op_sel_hi:[0,1]
	v_sub_f32_e32 v66, v95, v68
	v_exp_f32_e32 v93, v66
	v_sub_f32_e32 v66, v111, v68
	v_exp_f32_e32 v107, v66
	v_sub_f32_e32 v66, v96, v68
	v_exp_f32_e32 v94, v66
	v_sub_f32_e32 v66, v112, v68
	v_exp_f32_e32 v108, v66
	v_add_f32_e32 v95, v93, v107
	v_exp_f32_e64 v96, -v68
	v_add_f32_e32 v212, v97, v110
	v_pk_add_f32 v[66:67], v[94:95], v[108:109]
	v_cvt_pk_bf16_f32 v172, v92, v93
	v_pk_add_f32 v[66:67], v[66:67], v[66:67] op_sel:[0,1] op_sel_hi:[1,0]
	v_pk_mul_f32 v[48:49], v[48:49], v[96:97] op_sel_hi:[1,0]
	v_mov_b32_e32 v67, v68
	v_pk_add_f32 v[212:213], v[212:213], v[66:67]
	v_pk_mul_f32 v[46:47], v[46:47], v[96:97] op_sel_hi:[1,0]
	v_xor_b32_e32 v66, 0x80000000, v213
	v_mov_b32_e32 v67, v66
	v_mov_b32_e32 v68, v66
	v_mov_b32_e32 v69, v66
	v_mov_b32_e32 v70, v66
	v_mov_b32_e32 v71, v66
	v_mov_b32_e32 v72, v66
	v_mov_b32_e32 v73, v66
	v_mov_b32_e32 v74, v66
	v_mov_b32_e32 v75, v66
	v_mov_b32_e32 v76, v66
	v_mov_b32_e32 v77, v66
	v_mov_b32_e32 v78, v66
	v_mov_b32_e32 v79, v66
	v_mov_b32_e32 v80, v66
	v_mov_b32_e32 v81, v66
	v_pk_mul_f32 v[44:45], v[44:45], v[96:97] op_sel_hi:[1,0]
	v_pk_mul_f32 v[42:43], v[42:43], v[96:97] op_sel_hi:[1,0]
	v_pk_mul_f32 v[40:41], v[40:41], v[96:97] op_sel_hi:[1,0]
	v_pk_mul_f32 v[38:39], v[38:39], v[96:97] op_sel_hi:[1,0]
	v_pk_mul_f32 v[36:37], v[36:37], v[96:97] op_sel_hi:[1,0]
	v_pk_mul_f32 v[34:35], v[34:35], v[96:97] op_sel_hi:[1,0]
	v_pk_mul_f32 v[64:65], v[64:65], v[96:97] op_sel_hi:[1,0]
	v_pk_mul_f32 v[62:63], v[62:63], v[96:97] op_sel_hi:[1,0]
	v_pk_mul_f32 v[60:61], v[60:61], v[96:97] op_sel_hi:[1,0]
	v_pk_mul_f32 v[58:59], v[58:59], v[96:97] op_sel_hi:[1,0]
	v_pk_mul_f32 v[56:57], v[56:57], v[96:97] op_sel_hi:[1,0]
	v_pk_mul_f32 v[54:55], v[54:55], v[96:97] op_sel_hi:[1,0]
	v_pk_mul_f32 v[52:53], v[52:53], v[96:97] op_sel_hi:[1,0]
	v_pk_mul_f32 v[50:51], v[50:51], v[96:97] op_sel_hi:[1,0]
	v_pk_mul_f32 v[32:33], v[32:33], v[96:97] op_sel_hi:[1,0]
	v_pk_mul_f32 v[30:31], v[30:31], v[96:97] op_sel_hi:[1,0]
	v_pk_mul_f32 v[28:29], v[28:29], v[96:97] op_sel_hi:[1,0]
	v_pk_mul_f32 v[26:27], v[26:27], v[96:97] op_sel_hi:[1,0]
	v_pk_mul_f32 v[24:25], v[24:25], v[96:97] op_sel_hi:[1,0]
	v_pk_mul_f32 v[22:23], v[22:23], v[96:97] op_sel_hi:[1,0]
	v_pk_mul_f32 v[20:21], v[20:21], v[96:97] op_sel_hi:[1,0]
	v_pk_mul_f32 v[18:19], v[18:19], v[96:97] op_sel_hi:[1,0]
	v_pk_mul_f32 v[16:17], v[16:17], v[96:97] op_sel_hi:[1,0]
	v_pk_mul_f32 v[14:15], v[14:15], v[96:97] op_sel_hi:[1,0]
	v_pk_mul_f32 v[12:13], v[12:13], v[96:97] op_sel_hi:[1,0]
	v_pk_mul_f32 v[10:11], v[10:11], v[96:97] op_sel_hi:[1,0]
	v_pk_mul_f32 v[8:9], v[8:9], v[96:97] op_sel_hi:[1,0]
	v_pk_mul_f32 v[6:7], v[6:7], v[96:97] op_sel_hi:[1,0]
	v_pk_mul_f32 v[4:5], v[4:5], v[96:97] op_sel_hi:[1,0]
	v_pk_mul_f32 v[2:3], v[2:3], v[96:97] op_sel_hi:[1,0]
	v_mul_f32_e32 v242, v242, v96
	v_cvt_pk_bf16_f32 v173, v94, v97
	v_cvt_pk_bf16_f32 v186, v86, v105
	v_cvt_pk_bf16_f32 v187, v88, v91
	v_cvt_pk_bf16_f32 v188, v106, v107
	v_cvt_pk_bf16_f32 v189, v108, v110

.LBB0_291:
	s_waitcnt lgkmcnt(0)
	v_mfma_f32_32x32x16_bf16 v[50:65], v[126:129], v[162:165], v[50:65]
	ds_read_b128 v[126:129], v0 offset:49152
	s_nop 1
	v_exp_f32_e32 v130, v82
	v_exp_f32_e32 v131, v83
	v_add_f32_e32 v132, v1, v130
	v_add_f32_e32 v133, v1, v131
	v_cvt_pk_bf16_f32 v166, v130, v131
	v_mfma_f32_32x32x16_bf16 v[34:49], v[122:125], v[162:165], v[34:49]
	ds_read_b128 v[122:125], v0 offset:53248
	v_exp_f32_e32 v134, v84
	v_exp_f32_e32 v135, v85
	s_add_i32 s21, s22, 2
	s_cmp_lt_u32 s21, s18
	v_add_f32_e32 v130, v132, v134
	v_add_f32_e32 v131, v133, v135
	v_cvt_pk_bf16_f32 v167, v134, v135
	s_cselect_b64 s[26:27], -1, 0
	s_cmp_ge_u32 s21, s18
	s_cbranch_scc1 .LBB0_293
	v_lshl_add_u64 v[132:133], s[8:9], 0, v[214:215]
	s_lshl_b32 s37, s28, 14
	v_lshl_add_u64 v[132:133], v[132:133], 0, s[80:81]
	s_add_i32 m0, s10, s37
	s_nop 0
	global_load_lds_dwordx4 v[132:133], off
.LBB0_293:
	v_mfma_f32_32x32x16_bf16 v[18:33], v[118:121], v[162:165], v[18:33]
	ds_read_b128 v[118:121], v0 offset:57344
	v_exp_f32_e32 v132, v86
	v_exp_f32_e32 v133, v87
	v_add_f32_e32 v130, v130, v132
	v_add_f32_e32 v131, v131, v133
	v_cvt_pk_bf16_f32 v168, v132, v133
	v_mfma_f32_32x32x16_bf16 v[2:17], v[114:117], v[162:165], v[2:17]
	ds_read_b128 v[114:117], v0 offset:61440
	v_exp_f32_e32 v0, v88
	v_exp_f32_e32 v132, v89
	v_add_f32_e32 v130, v130, v0
	v_add_f32_e32 v131, v131, v132
	v_cvt_pk_bf16_f32 v169, v0, v132
	s_waitcnt lgkmcnt(0)
	v_mfma_f32_32x32x16_bf16 v[50:65], v[126:129], v[170:173], v[50:65]
	v_add_u32_e32 v0, s36, v247
	ds_read_b128 v[126:129], v0 offset:49152
	v_exp_f32_e32 v132, v90
	v_exp_f32_e32 v133, v91
	v_add_f32_e32 v130, v130, v132
	v_add_f32_e32 v131, v131, v133
	v_cvt_pk_bf16_f32 v174, v132, v133
	v_mfma_f32_32x32x16_bf16 v[34:49], v[122:125], v[170:173], v[34:49]
	ds_read_b128 v[122:125], v0 offset:53248
	v_exp_f32_e32 v132, v92
	v_exp_f32_e32 v133, v93
	v_add_f32_e32 v130, v130, v132
	v_add_f32_e32 v131, v131, v133
	s_andn2_b64 vcc, exec, s[26:27]
	v_cvt_pk_bf16_f32 v175, v132, v133
	s_cbranch_vccnz .LBB0_295
	s_lshl_b32 s26, s28, 14
	v_lshl_add_u64 v[132:133], s[8:9], 0, v[214:215]
	s_add_i32 s26, s10, s26
	v_lshl_add_u64 v[132:133], v[132:133], 0, s[62:63]
	s_add_i32 m0, s26, 0x2000
	s_nop 0
	global_load_lds_dwordx4 v[132:133], off
.LBB0_295:
	v_mfma_f32_32x32x16_bf16 v[18:33], v[118:121], v[170:173], v[18:33]
	ds_read_b128 v[118:121], v0 offset:57344
	v_exp_f32_e32 v132, v94
	v_exp_f32_e32 v133, v95
	v_add_f32_e32 v130, v130, v132
	v_add_f32_e32 v131, v131, v133
	v_cvt_pk_bf16_f32 v176, v132, v133
	v_mfma_f32_32x32x16_bf16 v[2:17], v[114:117], v[170:173], v[2:17]
	ds_read_b128 v[114:117], v0 offset:61440
	v_exp_f32_e32 v0, v96
	v_exp_f32_e32 v132, v97
	v_add_f32_e32 v130, v130, v0
	v_add_f32_e32 v131, v131, v132
	v_cvt_pk_bf16_f32 v177, v0, v132
	s_waitcnt lgkmcnt(0)
	v_mfma_f32_32x32x16_bf16 v[50:65], v[126:129], v[178:181], v[50:65]
	v_add_u32_e32 v0, s36, v248
	ds_read_b128 v[126:129], v0 offset:49152
	v_exp_f32_e32 v132, v98
	v_exp_f32_e32 v133, v99
	v_add_f32_e32 v130, v130, v132
	v_add_f32_e32 v131, v131, v133
	v_cvt_pk_bf16_f32 v182, v132, v133
	v_mfma_f32_32x32x16_bf16 v[34:49], v[122:125], v[178:181], v[34:49]
	v_exp_f32_e32 v132, v100
	v_exp_f32_e32 v133, v101
	ds_read_b128 v[122:125], v0 offset:53248
	v_add_f32_e32 v130, v130, v132
	v_add_f32_e32 v131, v131, v133
	v_cvt_pk_bf16_f32 v183, v132, v133
	v_cndmask_b32_e64 v132, 0, 1, s[44:45]
	v_cmp_ne_u32_e64 s[40:41], 1, v132
	s_andn2_b64 vcc, exec, s[44:45]
	s_cbranch_vccnz .LBB0_297
	s_lshl_b32 s26, s23, 14
	v_lshl_add_u64 v[132:133], s[8:9], 0, v[216:217]
	s_add_i32 s26, s10, s26
	v_lshl_add_u64 v[132:133], v[132:133], 0, s[96:97]
	s_add_i32 m0, s26, 0xc000
	s_nop 0
	global_load_lds_dwordx4 v[132:133], off
.LBB0_297:
	v_mfma_f32_32x32x16_bf16 v[18:33], v[118:121], v[178:181], v[18:33]
	ds_read_b128 v[118:121], v0 offset:57344
	v_exp_f32_e32 v132, v102
	v_exp_f32_e32 v133, v103
	v_add_f32_e32 v130, v130, v132
	v_add_f32_e32 v131, v131, v133
	v_cvt_pk_bf16_f32 v184, v132, v133
	v_mfma_f32_32x32x16_bf16 v[2:17], v[114:117], v[178:181], v[2:17]
	ds_read_b128 v[114:117], v0 offset:61440
	v_exp_f32_e32 v0, v104
	v_exp_f32_e32 v132, v105
	v_add_f32_e32 v130, v130, v0
	v_add_f32_e32 v131, v131, v132
	v_cvt_pk_bf16_f32 v185, v0, v132
	s_waitcnt lgkmcnt(0)
	v_mfma_f32_32x32x16_bf16 v[50:65], v[126:129], v[186:189], v[50:65]
	v_exp_f32_e32 v0, v106
	v_exp_f32_e32 v126, v107
	v_add_f32_e32 v127, v130, v0
	v_add_f32_e32 v128, v131, v126
	v_cvt_pk_bf16_f32 v190, v0, v126
	v_mfma_f32_32x32x16_bf16 v[34:49], v[122:125], v[186:189], v[34:49]
	v_exp_f32_e32 v123, v108
	v_exp_f32_e32 v124, v109
	v_add_f32_e32 v0, v127, v123
	v_add_f32_e32 v122, v128, v124
	s_and_b64 vcc, exec, s[40:41]
	v_cvt_pk_bf16_f32 v191, v123, v124
	s_cbranch_vccnz .LBB0_299
	s_lshl_b32 s26, s23, 14
	v_lshl_add_u64 v[124:125], s[8:9], 0, v[216:217]
	s_add_i32 s26, s10, s26
	v_lshl_add_u64 v[124:125], v[124:125], 0, s[58:59]
	s_add_i32 m0, s26, 0xe000
	s_nop 0
	global_load_lds_dwordx4 v[124:125], off
.LBB0_299:
	v_mfma_f32_32x32x16_bf16 v[18:33], v[118:121], v[186:189], v[18:33]
	v_exp_f32_e32 v118, v110
	v_exp_f32_e32 v119, v111
	v_add_f32_e32 v0, v0, v118
	v_add_f32_e32 v120, v122, v119
	v_cvt_pk_bf16_f32 v192, v118, v119
	v_mfma_f32_32x32x16_bf16 v[2:17], v[114:117], v[186:189], v[2:17]
	v_exp_f32_e32 v114, v112
	v_exp_f32_e32 v115, v113
	v_add_f32_e32 v0, v0, v114
	v_add_f32_e32 v116, v120, v115
	v_cvt_pk_bf16_f32 v193, v114, v115
	s_nop 0
	v_add_f32_e32 v212, v0, v116
	v_cmp_nge_f32_e32 vcc, s7, v212
	s_cbranch_vccz .LBB0_301
	v_max_f32_e32 v0, v99, v99
	v_max_f32_e32 v66, v83, v83
	v_max_f32_e32 v0, v66, v0
	v_max3_f32 v0, v82, v98, v0
	v_max3_f32 v66, v100, v85, v101
	v_max3_f32 v0, v0, v84, v66
	v_max3_f32 v66, v102, v87, v103
	v_max3_f32 v0, v0, v86, v66
	v_max3_f32 v66, v104, v89, v105
	v_max3_f32 v0, v0, v88, v66
	v_max3_f32 v66, v106, v91, v107
	v_max3_f32 v0, v0, v90, v66
	v_max3_f32 v66, v108, v93, v109
	v_max3_f32 v0, v0, v92, v66
	v_max3_f32 v66, v110, v95, v111
	v_max3_f32 v0, v0, v94, v66
	v_max3_f32 v66, v112, v97, v113
	v_max3_f32 v0, v0, v96, v66
	v_mov_b32_e32 v66, v0
	s_nop 1
	v_permlane32_swap_b32_e32 v0, v66
	v_max_f32_e32 v66, v66, v66
	v_max_f32_e32 v0, v0, v0
	v_max_f32_e32 v0, v0, v66
	v_cmp_lt_f32_e32 vcc, s57, v0
	s_nop 1
	v_cndmask_b32_e32 v68, 0, v0, vcc
	v_sub_f32_e32 v0, v82, v68
	v_exp_f32_e32 v116, v0
	v_sub_f32_e32 v0, v98, v68
	v_exp_f32_e32 v117, v0
	v_sub_f32_e32 v0, v83, v68
	v_exp_f32_e32 v118, v0
	v_sub_f32_e32 v0, v99, v68
	v_exp_f32_e32 v119, v0
	v_sub_f32_e32 v0, v84, v68
	v_exp_f32_e32 v98, v0
	v_sub_f32_e32 v0, v100, v68
	v_exp_f32_e32 v82, v0
	v_add_f32_e32 v0, v117, v116
	v_add_f32_e32 v99, 0, v0
	v_add_f32_e32 v83, v119, v118
	v_sub_f32_e32 v0, v85, v68
	v_pk_add_f32 v[66:67], v[82:83], v[98:99]
	v_exp_f32_e32 v83, v0
	v_sub_f32_e32 v0, v101, v68
	v_pk_add_f32 v[114:115], v[66:67], v[66:67] op_sel_hi:[0,1]
	v_exp_f32_e32 v99, v0
	v_sub_f32_e32 v0, v86, v68
	v_exp_f32_e32 v114, v0
	v_sub_f32_e32 v0, v102, v68
	v_exp_f32_e32 v84, v0
	v_add_f32_e32 v85, v99, v83
	v_sub_f32_e32 v0, v87, v68
	v_cvt_pk_bf16_f32 v166, v116, v118
	v_pk_add_f32 v[66:67], v[84:85], v[114:115]
	v_exp_f32_e32 v85, v0
	v_sub_f32_e32 v0, v103, v68
	v_pk_add_f32 v[100:101], v[66:67], v[66:67] op_sel_hi:[0,1]
	v_exp_f32_e32 v115, v0
	v_sub_f32_e32 v0, v88, v68
	v_exp_f32_e32 v100, v0
	v_sub_f32_e32 v0, v104, v68
	v_exp_f32_e32 v86, v0
	v_add_f32_e32 v87, v115, v85
	v_sub_f32_e32 v0, v89, v68
	v_cvt_pk_bf16_f32 v167, v98, v83
	v_pk_add_f32 v[66:67], v[86:87], v[100:101]
	v_exp_f32_e32 v87, v0
	v_sub_f32_e32 v0, v105, v68
	v_pk_add_f32 v[102:103], v[66:67], v[66:67] op_sel_hi:[0,1]
	v_exp_f32_e32 v101, v0
	v_sub_f32_e32 v0, v90, v68
	v_exp_f32_e32 v102, v0
	v_sub_f32_e32 v0, v106, v68
	v_exp_f32_e32 v88, v0
	v_add_f32_e32 v89, v101, v87
	v_sub_f32_e32 v0, v91, v68
	v_cvt_pk_bf16_f32 v168, v114, v85
	v_pk_add_f32 v[66:67], v[88:89], v[102:103]
	v_exp_f32_e32 v89, v0
	v_sub_f32_e32 v0, v107, v68
	v_pk_add_f32 v[104:105], v[66:67], v[66:67] op_sel_hi:[0,1]
	v_exp_f32_e32 v103, v0
	v_sub_f32_e32 v0, v92, v68
	v_exp_f32_e32 v104, v0
	v_sub_f32_e32 v0, v108, v68
	v_exp_f32_e32 v90, v0
	v_sub_f32_e32 v0, v97, v68
	v_exp_f32_e32 v97, v0
	v_add_f32_e32 v91, v103, v89
	v_sub_f32_e32 v0, v93, v68
	v_pk_add_f32 v[66:67], v[90:91], v[104:105]
	v_exp_f32_e32 v91, v0
	v_sub_f32_e32 v0, v109, v68
	v_pk_add_f32 v[106:107], v[66:67], v[66:67] op_sel_hi:[0,1]
	v_exp_f32_e32 v105, v0
	v_sub_f32_e32 v0, v94, v68
	v_exp_f32_e32 v106, v0
	v_sub_f32_e32 v0, v110, v68
	v_exp_f32_e32 v92, v0
	v_sub_f32_e32 v0, v113, v68
	v_exp_f32_e32 v110, v0
	v_add_f32_e32 v93, v105, v91
	v_sub_f32_e32 v0, v95, v68
	v_pk_add_f32 v[66:67], v[92:93], v[106:107]
	v_exp_f32_e32 v93, v0
	v_sub_f32_e32 v0, v111, v68
	v_pk_add_f32 v[108:109], v[66:67], v[66:67] op_sel_hi:[0,1]
	v_exp_f32_e32 v107, v0
	v_sub_f32_e32 v0, v96, v68
	v_exp_f32_e32 v108, v0
	v_sub_f32_e32 v0, v112, v68
	v_exp_f32_e32 v94, v0
	v_add_f32_e32 v95, v107, v93
	v_exp_f32_e64 v0, -v68
	v_add_f32_e32 v212, v110, v97
	v_pk_add_f32 v[66:67], v[94:95], v[108:109]
	v_cvt_pk_bf16_f32 v169, v100, v87
	v_pk_add_f32 v[66:67], v[66:67], v[66:67] op_sel:[0,1] op_sel_hi:[1,0]
	v_pk_mul_f32 v[64:65], v[64:65], v[0:1] op_sel_hi:[1,0]
	v_mov_b32_e32 v67, v68
	v_pk_add_f32 v[212:213], v[212:213], v[66:67]
	v_pk_mul_f32 v[62:63], v[62:63], v[0:1] op_sel_hi:[1,0]
	v_xor_b32_e32 v66, 0x80000000, v213
	v_mov_b32_e32 v67, v66
	v_mov_b32_e32 v68, v66
	v_mov_b32_e32 v69, v66
	v_mov_b32_e32 v70, v66
	v_mov_b32_e32 v71, v66
	v_mov_b32_e32 v72, v66
	v_mov_b32_e32 v73, v66
	v_mov_b32_e32 v74, v66
	v_mov_b32_e32 v75, v66
	v_mov_b32_e32 v76, v66
	v_mov_b32_e32 v77, v66
	v_mov_b32_e32 v78, v66
	v_mov_b32_e32 v79, v66
	v_mov_b32_e32 v80, v66
	v_mov_b32_e32 v81, v66
	v_pk_mul_f32 v[60:61], v[60:61], v[0:1] op_sel_hi:[1,0]
	v_pk_mul_f32 v[58:59], v[58:59], v[0:1] op_sel_hi:[1,0]
	v_pk_mul_f32 v[56:57], v[56:57], v[0:1] op_sel_hi:[1,0]
	v_pk_mul_f32 v[54:55], v[54:55], v[0:1] op_sel_hi:[1,0]
	v_pk_mul_f32 v[52:53], v[52:53], v[0:1] op_sel_hi:[1,0]
	v_pk_mul_f32 v[50:51], v[50:51], v[0:1] op_sel_hi:[1,0]
	v_pk_mul_f32 v[48:49], v[48:49], v[0:1] op_sel_hi:[1,0]
	v_pk_mul_f32 v[46:47], v[46:47], v[0:1] op_sel_hi:[1,0]
	v_pk_mul_f32 v[44:45], v[44:45], v[0:1] op_sel_hi:[1,0]
	v_pk_mul_f32 v[42:43], v[42:43], v[0:1] op_sel_hi:[1,0]
	v_pk_mul_f32 v[40:41], v[40:41], v[0:1] op_sel_hi:[1,0]
	v_pk_mul_f32 v[38:39], v[38:39], v[0:1] op_sel_hi:[1,0]
	v_pk_mul_f32 v[36:37], v[36:37], v[0:1] op_sel_hi:[1,0]
	v_pk_mul_f32 v[34:35], v[34:35], v[0:1] op_sel_hi:[1,0]
	v_pk_mul_f32 v[32:33], v[32:33], v[0:1] op_sel_hi:[1,0]
	v_pk_mul_f32 v[30:31], v[30:31], v[0:1] op_sel_hi:[1,0]
	v_pk_mul_f32 v[28:29], v[28:29], v[0:1] op_sel_hi:[1,0]
	v_pk_mul_f32 v[26:27], v[26:27], v[0:1] op_sel_hi:[1,0]
	v_pk_mul_f32 v[24:25], v[24:25], v[0:1] op_sel_hi:[1,0]
	v_pk_mul_f32 v[22:23], v[22:23], v[0:1] op_sel_hi:[1,0]
	v_pk_mul_f32 v[20:21], v[20:21], v[0:1] op_sel_hi:[1,0]
	v_pk_mul_f32 v[18:19], v[18:19], v[0:1] op_sel_hi:[1,0]
	v_pk_mul_f32 v[16:17], v[16:17], v[0:1] op_sel_hi:[1,0]
	v_pk_mul_f32 v[14:15], v[14:15], v[0:1] op_sel_hi:[1,0]
	v_pk_mul_f32 v[12:13], v[12:13], v[0:1] op_sel_hi:[1,0]
	v_pk_mul_f32 v[10:11], v[10:11], v[0:1] op_sel_hi:[1,0]
	v_pk_mul_f32 v[8:9], v[8:9], v[0:1] op_sel_hi:[1,0]
	v_pk_mul_f32 v[6:7], v[6:7], v[0:1] op_sel_hi:[1,0]
	v_pk_mul_f32 v[4:5], v[4:5], v[0:1] op_sel_hi:[1,0]
	v_pk_mul_f32 v[2:3], v[2:3], v[0:1] op_sel_hi:[1,0]
	v_mul_f32_e32 v243, v243, v0
	v_cvt_pk_bf16_f32 v174, v102, v89
	v_cvt_pk_bf16_f32 v175, v104, v91
	v_cvt_pk_bf16_f32 v176, v106, v93
	v_cvt_pk_bf16_f32 v177, v108, v97
	v_cvt_pk_bf16_f32 v182, v117, v119
	v_cvt_pk_bf16_f32 v183, v82, v99
	v_cvt_pk_bf16_f32 v184, v84, v115
	v_cvt_pk_bf16_f32 v185, v86, v101
	v_cvt_pk_bf16_f32 v190, v88, v103
	v_cvt_pk_bf16_f32 v191, v90, v105
	v_cvt_pk_bf16_f32 v192, v92, v107
	v_cvt_pk_bf16_f32 v193, v94, v110

.LBB0_331:
	s_waitcnt lgkmcnt(0)
	v_mfma_f32_32x32x16_bf16 v[50:65], v[126:129], v[166:169], v[50:65]
	ds_read_b128 v[126:129], v0 offset:49152
	s_nop 0
	v_exp_f32_e32 v130, v82
	v_exp_f32_e32 v131, v83
	v_add_f32_e32 v132, v1, v130
	v_add_f32_e32 v133, v1, v131
	v_cvt_pk_bf16_f32 v162, v130, v131
	v_mfma_f32_32x32x16_bf16 v[34:49], v[122:125], v[166:169], v[34:49]
	ds_read_b128 v[122:125], v0 offset:53248
	v_exp_f32_e32 v130, v84
	v_exp_f32_e32 v131, v85
	s_add_i32 s22, s22, 3
	s_cmp_le_u32 s22, s17
	v_add_f32_e32 v132, v132, v130
	v_add_f32_e32 v133, v133, v131
	v_cvt_pk_bf16_f32 v163, v130, v131
	s_cselect_b64 s[26:27], -1, 0
	s_cmp_gt_u32 s22, s17
	v_lshl_add_u64 v[130:131], s[8:9], 0, v[214:215]
	s_cbranch_scc1 .LBB0_333
	s_lshl_b32 s22, s28, 14
	v_lshl_add_u64 v[134:135], v[130:131], 0, s[50:51]
	s_add_i32 m0, s10, s22
	s_nop 0
	global_load_lds_dwordx4 v[134:135], off
.LBB0_333:
	v_mfma_f32_32x32x16_bf16 v[18:33], v[118:121], v[166:169], v[18:33]
	ds_read_b128 v[118:121], v0 offset:57344
	v_exp_f32_e32 v134, v86
	v_exp_f32_e32 v135, v87
	v_add_f32_e32 v132, v132, v134
	v_add_f32_e32 v133, v133, v135
	v_cvt_pk_bf16_f32 v164, v134, v135
	v_mfma_f32_32x32x16_bf16 v[2:17], v[114:117], v[166:169], v[2:17]
	ds_read_b128 v[114:117], v0 offset:61440
	v_exp_f32_e32 v0, v88
	v_exp_f32_e32 v134, v89
	v_add_f32_e32 v132, v132, v0
	v_add_f32_e32 v133, v133, v134
	v_cvt_pk_bf16_f32 v165, v0, v134
	s_waitcnt lgkmcnt(0)
	v_mfma_f32_32x32x16_bf16 v[50:65], v[126:129], v[174:177], v[50:65]
	v_add_u32_e32 v0, s36, v247
	ds_read_b128 v[126:129], v0 offset:49152
	v_exp_f32_e32 v134, v90
	v_exp_f32_e32 v135, v91
	v_add_f32_e32 v132, v132, v134
	v_add_f32_e32 v133, v133, v135
	v_cvt_pk_bf16_f32 v170, v134, v135
	v_mfma_f32_32x32x16_bf16 v[34:49], v[122:125], v[174:177], v[34:49]
	ds_read_b128 v[122:125], v0 offset:53248
	v_exp_f32_e32 v134, v92
	v_exp_f32_e32 v135, v93
	v_add_f32_e32 v132, v132, v134
	v_add_f32_e32 v133, v133, v135
	s_andn2_b64 vcc, exec, s[26:27]
	v_cvt_pk_bf16_f32 v171, v134, v135
	s_cbranch_vccnz .LBB0_335
	s_lshl_b32 s22, s28, 14
	s_add_i32 s22, s10, s22
	v_lshl_add_u64 v[130:131], v[130:131], 0, s[4:5]
	s_add_i32 m0, s22, 0x2000
	s_nop 0
	global_load_lds_dwordx4 v[130:131], off
.LBB0_335:
	v_mfma_f32_32x32x16_bf16 v[18:33], v[118:121], v[174:177], v[18:33]
	ds_read_b128 v[118:121], v0 offset:57344
	v_exp_f32_e32 v130, v94
	v_exp_f32_e32 v131, v95
	v_add_f32_e32 v132, v132, v130
	v_add_f32_e32 v133, v133, v131
	v_cvt_pk_bf16_f32 v172, v130, v131
	v_mfma_f32_32x32x16_bf16 v[2:17], v[114:117], v[174:177], v[2:17]
	ds_read_b128 v[114:117], v0 offset:61440
	v_exp_f32_e32 v0, v96
	v_exp_f32_e32 v130, v97
	v_add_f32_e32 v131, v132, v0
	v_add_f32_e32 v132, v133, v130
	v_cvt_pk_bf16_f32 v173, v0, v130
	s_waitcnt lgkmcnt(0)
	v_mfma_f32_32x32x16_bf16 v[50:65], v[126:129], v[182:185], v[50:65]
	v_add_u32_e32 v0, s36, v248
	ds_read_b128 v[126:129], v0 offset:49152
	v_exp_f32_e32 v130, v98
	v_exp_f32_e32 v133, v99
	v_add_f32_e32 v131, v131, v130
	v_add_f32_e32 v134, v132, v133
	v_cvt_pk_bf16_f32 v178, v130, v133
	v_mfma_f32_32x32x16_bf16 v[34:49], v[122:125], v[182:185], v[34:49]
	v_exp_f32_e32 v130, v100
	v_exp_f32_e32 v135, v101
	ds_read_b128 v[122:125], v0 offset:53248
	v_add_f32_e32 v132, v131, v130
	v_add_f32_e32 v133, v134, v135
	v_cvt_pk_bf16_f32 v179, v130, v135
	v_cndmask_b32_e64 v130, 0, 1, s[44:45]
	v_cmp_ne_u32_e64 s[40:41], 1, v130
	s_andn2_b64 vcc, exec, s[44:45]
	v_lshl_add_u64 v[130:131], s[8:9], 0, v[216:217]
	s_cbranch_vccnz .LBB0_337
	s_lshl_b32 s22, s23, 14
	s_add_i32 s22, s10, s22
	v_lshl_add_u64 v[134:135], v[130:131], 0, s[0:1]
	s_add_i32 m0, s22, 0xc000
	s_nop 0
	global_load_lds_dwordx4 v[134:135], off
.LBB0_337:
	v_mfma_f32_32x32x16_bf16 v[18:33], v[118:121], v[182:185], v[18:33]
	ds_read_b128 v[118:121], v0 offset:57344
	v_exp_f32_e32 v134, v102
	v_exp_f32_e32 v135, v103
	v_add_f32_e32 v132, v132, v134
	v_add_f32_e32 v133, v133, v135
	v_cvt_pk_bf16_f32 v180, v134, v135
	v_mfma_f32_32x32x16_bf16 v[2:17], v[114:117], v[182:185], v[2:17]
	ds_read_b128 v[114:117], v0 offset:61440
	v_exp_f32_e32 v0, v104
	v_exp_f32_e32 v134, v105
	v_add_f32_e32 v132, v132, v0
	v_add_f32_e32 v133, v133, v134
	v_cvt_pk_bf16_f32 v181, v0, v134
	s_waitcnt lgkmcnt(0)
	v_mfma_f32_32x32x16_bf16 v[50:65], v[126:129], v[190:193], v[50:65]
	v_exp_f32_e32 v0, v106
	v_exp_f32_e32 v126, v107
	v_add_f32_e32 v127, v132, v0
	v_add_f32_e32 v128, v133, v126
	v_cvt_pk_bf16_f32 v186, v0, v126
	v_mfma_f32_32x32x16_bf16 v[34:49], v[122:125], v[190:193], v[34:49]
	v_exp_f32_e32 v123, v108
	v_exp_f32_e32 v124, v109
	v_add_f32_e32 v0, v127, v123
	v_add_f32_e32 v122, v128, v124
	s_and_b64 vcc, exec, s[40:41]
	v_cvt_pk_bf16_f32 v187, v123, v124
	s_cbranch_vccnz .LBB0_339
	s_lshl_b32 s22, s23, 14
	s_add_i32 s22, s10, s22
	v_lshl_add_u64 v[124:125], v[130:131], 0, s[52:53]
	s_add_i32 m0, s22, 0xe000
	s_nop 0
	global_load_lds_dwordx4 v[124:125], off
.LBB0_339:
	v_mfma_f32_32x32x16_bf16 v[18:33], v[118:121], v[190:193], v[18:33]
	v_exp_f32_e32 v118, v110
	v_exp_f32_e32 v119, v111
	v_add_f32_e32 v0, v0, v118
	v_add_f32_e32 v120, v122, v119
	v_cvt_pk_bf16_f32 v188, v118, v119
	v_mfma_f32_32x32x16_bf16 v[2:17], v[114:117], v[190:193], v[2:17]
	v_exp_f32_e32 v114, v112
	v_exp_f32_e32 v115, v113
	v_add_f32_e32 v0, v0, v114
	v_add_f32_e32 v116, v120, v115
	v_cvt_pk_bf16_f32 v189, v114, v115
	s_nop 0
	v_add_f32_e32 v212, v0, v116
	v_cmp_nge_f32_e32 vcc, s7, v212
	s_cbranch_vccz .LBB0_341
	v_max_f32_e32 v0, v99, v99
	v_max_f32_e32 v66, v83, v83
	v_max_f32_e32 v0, v66, v0
	v_max3_f32 v0, v82, v98, v0
	v_max3_f32 v66, v100, v85, v101
	v_max3_f32 v0, v0, v84, v66
	v_max3_f32 v66, v102, v87, v103
	v_max3_f32 v0, v0, v86, v66
	v_max3_f32 v66, v104, v89, v105
	v_max3_f32 v0, v0, v88, v66
	v_max3_f32 v66, v106, v91, v107
	v_max3_f32 v0, v0, v90, v66
	v_max3_f32 v66, v108, v93, v109
	v_max3_f32 v0, v0, v92, v66
	v_max3_f32 v66, v110, v95, v111
	v_max3_f32 v0, v0, v94, v66
	v_max3_f32 v66, v112, v97, v113
	v_max3_f32 v0, v0, v96, v66
	v_mov_b32_e32 v66, v0
	s_nop 1
	v_permlane32_swap_b32_e32 v0, v66
	v_max_f32_e32 v66, v66, v66
	v_max_f32_e32 v0, v0, v0
	v_max_f32_e32 v0, v0, v66
	v_cmp_lt_f32_e32 vcc, s57, v0
	s_nop 1
	v_cndmask_b32_e32 v68, 0, v0, vcc
	v_sub_f32_e32 v0, v82, v68
	v_exp_f32_e32 v116, v0
	v_sub_f32_e32 v0, v98, v68
	v_exp_f32_e32 v117, v0
	v_sub_f32_e32 v0, v83, v68
	v_exp_f32_e32 v118, v0
	v_sub_f32_e32 v0, v99, v68
	v_exp_f32_e32 v119, v0
	v_sub_f32_e32 v0, v84, v68
	v_exp_f32_e32 v114, v0
	v_sub_f32_e32 v0, v100, v68
	v_exp_f32_e32 v82, v0
	v_add_f32_e32 v0, v116, v117
	v_add_f32_e32 v83, 0, v0
	v_add_f32_e32 v115, v118, v119
	v_sub_f32_e32 v0, v85, v68
	v_pk_add_f32 v[66:67], v[114:115], v[82:83]
	v_exp_f32_e32 v83, v0
	v_sub_f32_e32 v0, v101, v68
	v_exp_f32_e32 v115, v0
	v_sub_f32_e32 v0, v86, v68
	v_pk_add_f32 v[98:99], v[66:67], v[66:67] op_sel_hi:[0,1]
	v_exp_f32_e32 v100, v0
	v_sub_f32_e32 v0, v102, v68
	v_exp_f32_e32 v98, v0
	v_add_f32_e32 v101, v83, v115
	v_sub_f32_e32 v0, v87, v68
	v_cvt_pk_bf16_f32 v162, v116, v118
	v_pk_add_f32 v[66:67], v[100:101], v[98:99]
	v_exp_f32_e32 v99, v0
	v_sub_f32_e32 v0, v103, v68
	v_exp_f32_e32 v101, v0
	v_sub_f32_e32 v0, v88, v68
	v_pk_add_f32 v[84:85], v[66:67], v[66:67] op_sel_hi:[0,1]
	v_exp_f32_e32 v102, v0
	v_sub_f32_e32 v0, v104, v68
	v_exp_f32_e32 v84, v0
	v_add_f32_e32 v103, v99, v101
	v_sub_f32_e32 v0, v89, v68
	v_cvt_pk_bf16_f32 v163, v114, v83
	v_pk_add_f32 v[66:67], v[102:103], v[84:85]
	v_exp_f32_e32 v85, v0
	v_sub_f32_e32 v0, v105, v68
	v_exp_f32_e32 v103, v0
	v_sub_f32_e32 v0, v90, v68
	v_pk_add_f32 v[86:87], v[66:67], v[66:67] op_sel_hi:[0,1]
	v_exp_f32_e32 v104, v0
	v_sub_f32_e32 v0, v106, v68
	v_exp_f32_e32 v86, v0
	v_add_f32_e32 v105, v85, v103
	v_sub_f32_e32 v0, v91, v68
	v_cvt_pk_bf16_f32 v164, v100, v99
	v_pk_add_f32 v[66:67], v[104:105], v[86:87]
	v_exp_f32_e32 v87, v0
	v_sub_f32_e32 v0, v107, v68
	v_exp_f32_e32 v105, v0
	v_sub_f32_e32 v0, v92, v68
	v_pk_add_f32 v[88:89], v[66:67], v[66:67] op_sel_hi:[0,1]
	v_exp_f32_e32 v90, v0
	v_sub_f32_e32 v0, v108, v68
	v_exp_f32_e32 v88, v0
	v_sub_f32_e32 v0, v97, v68
	v_exp_f32_e32 v97, v0
	v_add_f32_e32 v91, v87, v105
	v_sub_f32_e32 v0, v93, v68
	v_pk_add_f32 v[66:67], v[90:91], v[88:89]
	v_exp_f32_e32 v89, v0
	v_sub_f32_e32 v0, v109, v68
	v_exp_f32_e32 v91, v0
	v_sub_f32_e32 v0, v94, v68
	v_pk_add_f32 v[106:107], v[66:67], v[66:67] op_sel_hi:[0,1]
	v_exp_f32_e32 v92, v0
	v_sub_f32_e32 v0, v110, v68
	v_exp_f32_e32 v106, v0
	v_sub_f32_e32 v0, v113, v68
	v_exp_f32_e32 v110, v0
	v_add_f32_e32 v93, v89, v91
	v_sub_f32_e32 v0, v95, v68
	v_pk_add_f32 v[66:67], v[92:93], v[106:107]
	v_exp_f32_e32 v93, v0
	v_sub_f32_e32 v0, v111, v68
	v_exp_f32_e32 v107, v0
	v_sub_f32_e32 v0, v96, v68
	v_pk_add_f32 v[108:109], v[66:67], v[66:67] op_sel_hi:[0,1]
	v_exp_f32_e32 v94, v0
	v_sub_f32_e32 v0, v112, v68
	v_exp_f32_e32 v108, v0
	v_add_f32_e32 v95, v93, v107
	v_exp_f32_e64 v0, -v68
	v_add_f32_e32 v212, v97, v110
	v_pk_add_f32 v[66:67], v[94:95], v[108:109]
	v_cvt_pk_bf16_f32 v165, v102, v85
	v_pk_add_f32 v[66:67], v[66:67], v[66:67] op_sel:[0,1] op_sel_hi:[1,0]
	v_pk_mul_f32 v[64:65], v[64:65], v[0:1] op_sel_hi:[1,0]
	v_mov_b32_e32 v67, v68
	v_pk_add_f32 v[212:213], v[212:213], v[66:67]
	v_pk_mul_f32 v[62:63], v[62:63], v[0:1] op_sel_hi:[1,0]
	v_xor_b32_e32 v66, 0x80000000, v213
	v_mov_b32_e32 v67, v66
	v_mov_b32_e32 v68, v66
	v_mov_b32_e32 v69, v66
	v_mov_b32_e32 v70, v66
	v_mov_b32_e32 v71, v66
	v_mov_b32_e32 v72, v66
	v_mov_b32_e32 v73, v66
	v_mov_b32_e32 v74, v66
	v_mov_b32_e32 v75, v66
	v_mov_b32_e32 v76, v66
	v_mov_b32_e32 v77, v66
	v_mov_b32_e32 v78, v66
	v_mov_b32_e32 v79, v66
	v_mov_b32_e32 v80, v66
	v_mov_b32_e32 v81, v66
	v_pk_mul_f32 v[60:61], v[60:61], v[0:1] op_sel_hi:[1,0]
	v_pk_mul_f32 v[58:59], v[58:59], v[0:1] op_sel_hi:[1,0]
	v_pk_mul_f32 v[56:57], v[56:57], v[0:1] op_sel_hi:[1,0]
	v_pk_mul_f32 v[54:55], v[54:55], v[0:1] op_sel_hi:[1,0]
	v_pk_mul_f32 v[52:53], v[52:53], v[0:1] op_sel_hi:[1,0]
	v_pk_mul_f32 v[50:51], v[50:51], v[0:1] op_sel_hi:[1,0]
	v_pk_mul_f32 v[48:49], v[48:49], v[0:1] op_sel_hi:[1,0]
	v_pk_mul_f32 v[46:47], v[46:47], v[0:1] op_sel_hi:[1,0]
	v_pk_mul_f32 v[44:45], v[44:45], v[0:1] op_sel_hi:[1,0]
	v_pk_mul_f32 v[42:43], v[42:43], v[0:1] op_sel_hi:[1,0]
	v_pk_mul_f32 v[40:41], v[40:41], v[0:1] op_sel_hi:[1,0]
	v_pk_mul_f32 v[38:39], v[38:39], v[0:1] op_sel_hi:[1,0]
	v_pk_mul_f32 v[36:37], v[36:37], v[0:1] op_sel_hi:[1,0]
	v_pk_mul_f32 v[34:35], v[34:35], v[0:1] op_sel_hi:[1,0]
	v_pk_mul_f32 v[32:33], v[32:33], v[0:1] op_sel_hi:[1,0]
	v_pk_mul_f32 v[30:31], v[30:31], v[0:1] op_sel_hi:[1,0]
	v_pk_mul_f32 v[28:29], v[28:29], v[0:1] op_sel_hi:[1,0]
	v_pk_mul_f32 v[26:27], v[26:27], v[0:1] op_sel_hi:[1,0]
	v_pk_mul_f32 v[24:25], v[24:25], v[0:1] op_sel_hi:[1,0]
	v_pk_mul_f32 v[22:23], v[22:23], v[0:1] op_sel_hi:[1,0]
	v_pk_mul_f32 v[20:21], v[20:21], v[0:1] op_sel_hi:[1,0]
	v_pk_mul_f32 v[18:19], v[18:19], v[0:1] op_sel_hi:[1,0]
	v_pk_mul_f32 v[16:17], v[16:17], v[0:1] op_sel_hi:[1,0]
	v_pk_mul_f32 v[14:15], v[14:15], v[0:1] op_sel_hi:[1,0]
	v_pk_mul_f32 v[12:13], v[12:13], v[0:1] op_sel_hi:[1,0]
	v_pk_mul_f32 v[10:11], v[10:11], v[0:1] op_sel_hi:[1,0]
	v_pk_mul_f32 v[8:9], v[8:9], v[0:1] op_sel_hi:[1,0]
	v_pk_mul_f32 v[6:7], v[6:7], v[0:1] op_sel_hi:[1,0]
	v_pk_mul_f32 v[4:5], v[4:5], v[0:1] op_sel_hi:[1,0]
	v_pk_mul_f32 v[2:3], v[2:3], v[0:1] op_sel_hi:[1,0]
	v_mul_f32_e32 v243, v243, v0
	v_cvt_pk_bf16_f32 v170, v104, v87
	v_cvt_pk_bf16_f32 v171, v90, v89
	v_cvt_pk_bf16_f32 v172, v92, v93
	v_cvt_pk_bf16_f32 v173, v94, v97
	v_cvt_pk_bf16_f32 v178, v117, v119
	v_cvt_pk_bf16_f32 v179, v82, v115
	v_cvt_pk_bf16_f32 v180, v98, v101
	v_cvt_pk_bf16_f32 v181, v84, v103
	v_cvt_pk_bf16_f32 v186, v86, v105
	v_cvt_pk_bf16_f32 v187, v88, v91
	v_cvt_pk_bf16_f32 v188, v106, v107
	v_cvt_pk_bf16_f32 v189, v108, v110
